# 64-byte alignment of the six GEMM main-loop heads and the attention loop body (on top of lambda hoist)
# speedup vs baseline: 1.0050x; 1.0050x over previous
; template <class Epi, class Sched, bool ALIGN_EPI = false, bool SP2 = false>
; __device__ __forceinline__ void gemm_phase(PG8_LAS unsigned char* lds, const Gemm g, const Sched& S, const Epi& E, int wave_s) {
;     ...
;         const bool has_next = S.next(ui + 1, nxt);
;         const char* nA = has_next ? (const char*)g.A + (size_t)nxt.pm * tstep : cA; const char* nB = has_next ? (const char*)g.Bt + (size_t)nxt.pn * tstep : cB;
;         for (int t = 0; t < nt; t += 2) {
;     ...
; #pragma unroll
;         for (int a = 0; a < 2; ++a)
; #pragma unroll
;             for (int b = 0; b < 2; ++b)
; #pragma unroll
;                 for (int m = 0; m < 4; ++m)
; #pragma unroll
;                     for (int n = 0; n < 2; ++n) acc[a][b][m][n] = (f32x4){0.f, 0.f, 0.f, 0.f};
.LBB0_119:
	s_ashr_i32 s69, s68, 31
	s_lshl_b64 s[8:9], s[68:69], 19
	s_add_u32 s70, s28, s8
	s_addc_u32 s71, s29, s9
	s_and_b64 s[8:9], s[0:1], exec
	s_cselect_b32 s3, s71, s5
	s_cselect_b32 s10, s70, s4
	s_ashr_i32 s67, s66, 31
	s_lshl_b64 s[8:9], s[66:67], 19
	s_add_u32 s72, s88, s8
	s_addc_u32 s73, s89, s9
	s_and_b64 s[8:9], s[0:1], exec
	s_cselect_b32 s11, s73, s7
	s_cselect_b32 s12, s72, s6
	s_add_u32 s4, s4, 0x40080
	s_addc_u32 s5, s5, 0
	s_add_u32 s47, s6, 0x100
	v_mov_b32_e32 v4, 0
	s_addc_u32 s57, s7, 0
	s_mov_b32 s67, -2
	v_mov_b32_e32 v5, v4
	v_mov_b32_e32 v6, v4
	v_mov_b32_e32 v7, v4
	v_mov_b32_e32 v0, v4
	v_mov_b32_e32 v1, v4
	v_mov_b32_e32 v2, v4
	v_mov_b32_e32 v3, v4
	v_mov_b32_e32 v20, v4
	v_mov_b32_e32 v21, v4
	v_mov_b32_e32 v22, v4
	v_mov_b32_e32 v23, v4
	v_mov_b32_e32 v16, v4
	v_mov_b32_e32 v17, v4
	v_mov_b32_e32 v18, v4
	v_mov_b32_e32 v19, v4
	v_mov_b32_e32 v36, v4
	v_mov_b32_e32 v37, v4
	v_mov_b32_e32 v38, v4
	v_mov_b32_e32 v39, v4
	v_mov_b32_e32 v32, v4
	v_mov_b32_e32 v33, v4
	v_mov_b32_e32 v34, v4
	v_mov_b32_e32 v35, v4
	v_mov_b32_e32 v52, v4
	v_mov_b32_e32 v53, v4
	v_mov_b32_e32 v54, v4
	v_mov_b32_e32 v55, v4
	v_mov_b32_e32 v48, v4
	v_mov_b32_e32 v49, v4
	v_mov_b32_e32 v50, v4
	v_mov_b32_e32 v51, v4
	v_mov_b32_e32 v8, v4
	v_mov_b32_e32 v9, v4
	v_mov_b32_e32 v10, v4
	v_mov_b32_e32 v11, v4
	v_mov_b32_e32 v12, v4
	v_mov_b32_e32 v13, v4
	v_mov_b32_e32 v14, v4
	v_mov_b32_e32 v15, v4
	v_mov_b32_e32 v24, v4
	v_mov_b32_e32 v25, v4
	v_mov_b32_e32 v26, v4
	v_mov_b32_e32 v27, v4
	v_mov_b32_e32 v28, v4
	v_mov_b32_e32 v29, v4
	v_mov_b32_e32 v30, v4
	v_mov_b32_e32 v31, v4
	v_mov_b32_e32 v40, v4
	v_mov_b32_e32 v41, v4
	v_mov_b32_e32 v42, v4
	v_mov_b32_e32 v43, v4
	v_mov_b32_e32 v44, v4
	v_mov_b32_e32 v45, v4
	v_mov_b32_e32 v46, v4
	v_mov_b32_e32 v47, v4
	v_mov_b32_e32 v56, v4
	v_mov_b32_e32 v57, v4
	v_mov_b32_e32 v58, v4
	v_mov_b32_e32 v59, v4
	v_mov_b32_e32 v60, v4
	v_mov_b32_e32 v61, v4
	v_mov_b32_e32 v62, v4
	v_mov_b32_e32 v63, v4
	v_mov_b32_e32 v68, v4
	v_mov_b32_e32 v69, v4
	v_mov_b32_e32 v70, v4
	v_mov_b32_e32 v71, v4
	v_mov_b32_e32 v64, v4
	v_mov_b32_e32 v65, v4
	v_mov_b32_e32 v66, v4
	v_mov_b32_e32 v67, v4
	v_mov_b32_e32 v84, v4
	v_mov_b32_e32 v85, v4
	v_mov_b32_e32 v86, v4
	v_mov_b32_e32 v87, v4
	v_mov_b32_e32 v80, v4
	v_mov_b32_e32 v81, v4
	v_mov_b32_e32 v82, v4
	v_mov_b32_e32 v83, v4
	v_mov_b32_e32 v100, v4
	v_mov_b32_e32 v101, v4
	v_mov_b32_e32 v102, v4
	v_mov_b32_e32 v103, v4
	v_mov_b32_e32 v96, v4
	v_mov_b32_e32 v97, v4
	v_mov_b32_e32 v98, v4
	v_mov_b32_e32 v99, v4
	v_mov_b32_e32 v112, v4
	v_mov_b32_e32 v113, v4
	v_mov_b32_e32 v114, v4
	v_mov_b32_e32 v115, v4
	v_mov_b32_e32 v116, v4
	v_mov_b32_e32 v117, v4
	v_mov_b32_e32 v118, v4
	v_mov_b32_e32 v119, v4
	v_mov_b32_e32 v72, v4
	v_mov_b32_e32 v73, v4
	v_mov_b32_e32 v74, v4
	v_mov_b32_e32 v75, v4
	v_mov_b32_e32 v76, v4
	v_mov_b32_e32 v77, v4
	v_mov_b32_e32 v78, v4
	v_mov_b32_e32 v79, v4
	v_mov_b32_e32 v88, v4
	v_mov_b32_e32 v89, v4
	v_mov_b32_e32 v90, v4
	v_mov_b32_e32 v91, v4
	v_mov_b32_e32 v92, v4
	v_mov_b32_e32 v93, v4
	v_mov_b32_e32 v94, v4
	v_mov_b32_e32 v95, v4
	v_mov_b32_e32 v104, v4
	v_mov_b32_e32 v105, v4
	v_mov_b32_e32 v106, v4
	v_mov_b32_e32 v107, v4
	v_mov_b32_e32 v108, v4
	v_mov_b32_e32 v109, v4
	v_mov_b32_e32 v110, v4
	v_mov_b32_e32 v111, v4
	v_mov_b32_e32 v120, v4
	v_mov_b32_e32 v121, v4
	v_mov_b32_e32 v122, v4
	v_mov_b32_e32 v123, v4
	v_mov_b32_e32 v124, v4
	v_mov_b32_e32 v125, v4
	v_mov_b32_e32 v126, v4
	v_mov_b32_e32 v127, v4
	.p2alignl 6, 3212836864

; template <bool SAMPLE> __device__ __forceinline__ void attn_unit16(const Ctx& c, LAS unsigned char* lds, int b, int h, int qb, int wave_s) {
;     ...
;     for (int j = 0; j < ntiles; j += 2) {
;         ITER16(j, pfa, pfb, 0, 1);
;         if (j + 1 < ntiles) ITER16(j + 1, pfb, pfa, 1, 0);
;     }
.LBB0_836:
	s_add_i32 s88, s89, 2
	s_cmp_lt_u32 s88, s84
	s_cbranch_scc0 .Lq1_last
	.p2alignl 6, 3212836864

; template <class Epi, class Sched, bool ALIGN_EPI = false, bool SP2 = false>
; __device__ __forceinline__ void gemm_phase(PG8_LAS unsigned char* lds, const Gemm g, const Sched& S, const Epi& E, int wave_s) {
;     ...
;         const bool has_next = S.next(ui + 1, nxt);
;         const char* nA = has_next ? (const char*)g.A + (size_t)nxt.pm * tstep : cA; const char* nB = has_next ? (const char*)g.Bt + (size_t)nxt.pn * tstep : cB;
;         for (int t = 0; t < nt; t += 2) {
;     ...
; #pragma unroll
;         for (int a = 0; a < 2; ++a)
; #pragma unroll
;             for (int b = 0; b < 2; ++b)
; #pragma unroll
;                 for (int m = 0; m < 4; ++m)
; #pragma unroll
;                     for (int n = 0; n < 2; ++n) acc[a][b][m][n] = (f32x4){0.f, 0.f, 0.f, 0.f};
.LBB0_1025:
	s_ashr_i32 s19, s18, 31
	s_lshl_b64 s[20:21], s[18:19], 19
	s_add_u32 s20, s46, s20
	s_addc_u32 s21, s47, s21
	s_and_b64 s[22:23], s[0:1], exec
	s_cselect_b32 s19, s21, s27
	s_cselect_b32 s69, s20, s26
	s_ashr_i32 s17, s16, 31
	s_lshl_b64 s[22:23], s[16:17], 19
	s_add_u32 s22, s45, s22
	s_addc_u32 s23, s48, s23
	s_and_b64 s[42:43], s[0:1], exec
	s_cselect_b32 s17, s23, s41
	s_cselect_b32 s70, s22, s40
	s_add_u32 s26, s26, 0x40080
	s_addc_u32 s27, s27, 0
	s_add_u32 s71, s40, 0x100
	v_mov_b32_e32 v0, 0
	s_addc_u32 s72, s41, 0
	s_mov_b32 s73, -2
	v_mov_b32_e32 v1, v0
	v_mov_b32_e32 v2, v0
	v_mov_b32_e32 v3, v0
	v_mov_b32_e32 v4, v0
	v_mov_b32_e32 v5, v0
	v_mov_b32_e32 v6, v0
	v_mov_b32_e32 v7, v0
	v_mov_b32_e32 v16, v0
	v_mov_b32_e32 v17, v0
	v_mov_b32_e32 v18, v0
	v_mov_b32_e32 v19, v0
	v_mov_b32_e32 v20, v0
	v_mov_b32_e32 v21, v0
	v_mov_b32_e32 v22, v0
	v_mov_b32_e32 v23, v0
	v_mov_b32_e32 v32, v0
	v_mov_b32_e32 v33, v0
	v_mov_b32_e32 v34, v0
	v_mov_b32_e32 v35, v0
	v_mov_b32_e32 v36, v0
	v_mov_b32_e32 v37, v0
	v_mov_b32_e32 v38, v0
	v_mov_b32_e32 v39, v0
	v_mov_b32_e32 v48, v0
	v_mov_b32_e32 v49, v0
	v_mov_b32_e32 v50, v0
	v_mov_b32_e32 v51, v0
	v_mov_b32_e32 v52, v0
	v_mov_b32_e32 v53, v0
	v_mov_b32_e32 v54, v0
	v_mov_b32_e32 v55, v0
	v_mov_b32_e32 v8, v0
	v_mov_b32_e32 v9, v0
	v_mov_b32_e32 v10, v0
	v_mov_b32_e32 v11, v0
	v_mov_b32_e32 v12, v0
	v_mov_b32_e32 v13, v0
	v_mov_b32_e32 v14, v0
	v_mov_b32_e32 v15, v0
	v_mov_b32_e32 v24, v0
	v_mov_b32_e32 v25, v0
	v_mov_b32_e32 v26, v0
	v_mov_b32_e32 v27, v0
	v_mov_b32_e32 v28, v0
	v_mov_b32_e32 v29, v0
	v_mov_b32_e32 v30, v0
	v_mov_b32_e32 v31, v0
	v_mov_b32_e32 v40, v0
	v_mov_b32_e32 v41, v0
	v_mov_b32_e32 v42, v0
	v_mov_b32_e32 v43, v0
	v_mov_b32_e32 v44, v0
	v_mov_b32_e32 v45, v0
	v_mov_b32_e32 v46, v0
	v_mov_b32_e32 v47, v0
	v_mov_b32_e32 v56, v0
	v_mov_b32_e32 v57, v0
	v_mov_b32_e32 v58, v0
	v_mov_b32_e32 v59, v0
	v_mov_b32_e32 v60, v0
	v_mov_b32_e32 v61, v0
	v_mov_b32_e32 v62, v0
	v_mov_b32_e32 v63, v0
	v_mov_b32_e32 v64, v0
	v_mov_b32_e32 v65, v0
	v_mov_b32_e32 v66, v0
	v_mov_b32_e32 v67, v0
	v_mov_b32_e32 v68, v0
	v_mov_b32_e32 v69, v0
	v_mov_b32_e32 v70, v0
	v_mov_b32_e32 v71, v0
	v_mov_b32_e32 v80, v0
	v_mov_b32_e32 v81, v0
	v_mov_b32_e32 v82, v0
	v_mov_b32_e32 v83, v0
	v_mov_b32_e32 v84, v0
	v_mov_b32_e32 v85, v0
	v_mov_b32_e32 v86, v0
	v_mov_b32_e32 v87, v0
	v_mov_b32_e32 v96, v0
	v_mov_b32_e32 v97, v0
	v_mov_b32_e32 v98, v0
	v_mov_b32_e32 v99, v0
	v_mov_b32_e32 v100, v0
	v_mov_b32_e32 v101, v0
	v_mov_b32_e32 v102, v0
	v_mov_b32_e32 v103, v0
	v_mov_b32_e32 v112, v0
	v_mov_b32_e32 v113, v0
	v_mov_b32_e32 v114, v0
	v_mov_b32_e32 v115, v0
	v_mov_b32_e32 v116, v0
	v_mov_b32_e32 v117, v0
	v_mov_b32_e32 v118, v0
	v_mov_b32_e32 v119, v0
	v_mov_b32_e32 v72, v0
	v_mov_b32_e32 v73, v0
	v_mov_b32_e32 v74, v0
	v_mov_b32_e32 v75, v0
	v_mov_b32_e32 v76, v0
	v_mov_b32_e32 v77, v0
	v_mov_b32_e32 v78, v0
	v_mov_b32_e32 v79, v0
	v_mov_b32_e32 v88, v0
	v_mov_b32_e32 v89, v0
	v_mov_b32_e32 v90, v0
	v_mov_b32_e32 v91, v0
	v_mov_b32_e32 v92, v0
	v_mov_b32_e32 v93, v0
	v_mov_b32_e32 v94, v0
	v_mov_b32_e32 v95, v0
	v_mov_b32_e32 v104, v0
	v_mov_b32_e32 v105, v0
	v_mov_b32_e32 v106, v0
	v_mov_b32_e32 v107, v0
	v_mov_b32_e32 v108, v0
	v_mov_b32_e32 v109, v0
	v_mov_b32_e32 v110, v0
	v_mov_b32_e32 v111, v0
	v_mov_b32_e32 v120, v0
	v_mov_b32_e32 v121, v0
	v_mov_b32_e32 v122, v0
	v_mov_b32_e32 v123, v0
	v_mov_b32_e32 v124, v0
	v_mov_b32_e32 v125, v0
	v_mov_b32_e32 v126, v0
	v_mov_b32_e32 v127, v0
	.p2alignl 6, 3212836864

; template <class Epi, class Sched, bool ALIGN_EPI = false, bool SP2 = false>
; __device__ __forceinline__ void gemm_phase(PG8_LAS unsigned char* lds, const Gemm g, const Sched& S, const Epi& E, int wave_s) {
;     ...
;         const bool has_next = S.next(ui + 1, nxt);
;         const char* nA = has_next ? (const char*)g.A + (size_t)nxt.pm * tstep : cA; const char* nB = has_next ? (const char*)g.Bt + (size_t)nxt.pn * tstep : cB;
;         for (int t = 0; t < nt; t += 2) {
;     ...
; #pragma unroll
;         for (int a = 0; a < 2; ++a)
; #pragma unroll
;             for (int b = 0; b < 2; ++b)
; #pragma unroll
;                 for (int m = 0; m < 4; ++m)
; #pragma unroll
;                     for (int n = 0; n < 2; ++n) acc[a][b][m][n] = (f32x4){0.f, 0.f, 0.f, 0.f};
.LBB0_1052:
	s_ashr_i32 s17, s16, 31
	s_lshl_b64 s[18:19], s[16:17], 19
	s_add_u32 s18, s92, s18
	s_addc_u32 s19, s93, s19
	s_and_b64 s[20:21], s[2:3], exec
	s_cselect_b32 s17, s19, s25
	s_cselect_b32 s66, s18, s24
	s_ashr_i32 s13, s12, 31
	s_lshl_b64 s[20:21], s[12:13], 19
	s_add_u32 s20, s44, s20
	s_addc_u32 s21, s45, s21
	s_and_b64 s[40:41], s[2:3], exec
	s_cselect_b32 s13, s21, s27
	s_cselect_b32 s67, s20, s26
	s_add_u32 s24, s24, 0x40080
	s_addc_u32 s25, s25, 0
	s_add_u32 s68, s26, 0x100
	v_mov_b32_e32 v0, 0
	s_addc_u32 s69, s27, 0
	s_mov_b32 s70, -2
	v_mov_b32_e32 v1, v0
	v_mov_b32_e32 v2, v0
	v_mov_b32_e32 v3, v0
	v_mov_b32_e32 v4, v0
	v_mov_b32_e32 v5, v0
	v_mov_b32_e32 v6, v0
	v_mov_b32_e32 v7, v0
	v_mov_b32_e32 v16, v0
	v_mov_b32_e32 v17, v0
	v_mov_b32_e32 v18, v0
	v_mov_b32_e32 v19, v0
	v_mov_b32_e32 v20, v0
	v_mov_b32_e32 v21, v0
	v_mov_b32_e32 v22, v0
	v_mov_b32_e32 v23, v0
	v_mov_b32_e32 v32, v0
	v_mov_b32_e32 v33, v0
	v_mov_b32_e32 v34, v0
	v_mov_b32_e32 v35, v0
	v_mov_b32_e32 v36, v0
	v_mov_b32_e32 v37, v0
	v_mov_b32_e32 v38, v0
	v_mov_b32_e32 v39, v0
	v_mov_b32_e32 v48, v0
	v_mov_b32_e32 v49, v0
	v_mov_b32_e32 v50, v0
	v_mov_b32_e32 v51, v0
	v_mov_b32_e32 v52, v0
	v_mov_b32_e32 v53, v0
	v_mov_b32_e32 v54, v0
	v_mov_b32_e32 v55, v0
	v_mov_b32_e32 v8, v0
	v_mov_b32_e32 v9, v0
	v_mov_b32_e32 v10, v0
	v_mov_b32_e32 v11, v0
	v_mov_b32_e32 v12, v0
	v_mov_b32_e32 v13, v0
	v_mov_b32_e32 v14, v0
	v_mov_b32_e32 v15, v0
	v_mov_b32_e32 v24, v0
	v_mov_b32_e32 v25, v0
	v_mov_b32_e32 v26, v0
	v_mov_b32_e32 v27, v0
	v_mov_b32_e32 v28, v0
	v_mov_b32_e32 v29, v0
	v_mov_b32_e32 v30, v0
	v_mov_b32_e32 v31, v0
	v_mov_b32_e32 v40, v0
	v_mov_b32_e32 v41, v0
	v_mov_b32_e32 v42, v0
	v_mov_b32_e32 v43, v0
	v_mov_b32_e32 v44, v0
	v_mov_b32_e32 v45, v0
	v_mov_b32_e32 v46, v0
	v_mov_b32_e32 v47, v0
	v_mov_b32_e32 v56, v0
	v_mov_b32_e32 v57, v0
	v_mov_b32_e32 v58, v0
	v_mov_b32_e32 v59, v0
	v_mov_b32_e32 v60, v0
	v_mov_b32_e32 v61, v0
	v_mov_b32_e32 v62, v0
	v_mov_b32_e32 v63, v0
	v_mov_b32_e32 v64, v0
	v_mov_b32_e32 v65, v0
	v_mov_b32_e32 v66, v0
	v_mov_b32_e32 v67, v0
	v_mov_b32_e32 v68, v0
	v_mov_b32_e32 v69, v0
	v_mov_b32_e32 v70, v0
	v_mov_b32_e32 v71, v0
	v_mov_b32_e32 v80, v0
	v_mov_b32_e32 v81, v0
	v_mov_b32_e32 v82, v0
	v_mov_b32_e32 v83, v0
	v_mov_b32_e32 v84, v0
	v_mov_b32_e32 v85, v0
	v_mov_b32_e32 v86, v0
	v_mov_b32_e32 v87, v0
	v_mov_b32_e32 v96, v0
	v_mov_b32_e32 v97, v0
	v_mov_b32_e32 v98, v0
	v_mov_b32_e32 v99, v0
	v_mov_b32_e32 v100, v0
	v_mov_b32_e32 v101, v0
	v_mov_b32_e32 v102, v0
	v_mov_b32_e32 v103, v0
	v_mov_b32_e32 v112, v0
	v_mov_b32_e32 v113, v0
	v_mov_b32_e32 v114, v0
	v_mov_b32_e32 v115, v0
	v_mov_b32_e32 v116, v0
	v_mov_b32_e32 v117, v0
	v_mov_b32_e32 v118, v0
	v_mov_b32_e32 v119, v0
	v_mov_b32_e32 v72, v0
	v_mov_b32_e32 v73, v0
	v_mov_b32_e32 v74, v0
	v_mov_b32_e32 v75, v0
	v_mov_b32_e32 v76, v0
	v_mov_b32_e32 v77, v0
	v_mov_b32_e32 v78, v0
	v_mov_b32_e32 v79, v0
	v_mov_b32_e32 v88, v0
	v_mov_b32_e32 v89, v0
	v_mov_b32_e32 v90, v0
	v_mov_b32_e32 v91, v0
	v_mov_b32_e32 v92, v0
	v_mov_b32_e32 v93, v0
	v_mov_b32_e32 v94, v0
	v_mov_b32_e32 v95, v0
	v_mov_b32_e32 v104, v0
	v_mov_b32_e32 v105, v0
	v_mov_b32_e32 v106, v0
	v_mov_b32_e32 v107, v0
	v_mov_b32_e32 v108, v0
	v_mov_b32_e32 v109, v0
	v_mov_b32_e32 v110, v0
	v_mov_b32_e32 v111, v0
	v_mov_b32_e32 v120, v0
	v_mov_b32_e32 v121, v0
	v_mov_b32_e32 v122, v0
	v_mov_b32_e32 v123, v0
	v_mov_b32_e32 v124, v0
	v_mov_b32_e32 v125, v0
	v_mov_b32_e32 v126, v0
	v_mov_b32_e32 v127, v0
	.p2alignl 6, 3212836864

; template <class Epi, class Sched, bool ALIGN_EPI = false, bool SP2 = false>
; __device__ __forceinline__ void gemm_phase(PG8_LAS unsigned char* lds, const Gemm g, const Sched& S, const Epi& E, int wave_s) {
;     ...
;         const bool has_next = S.next(ui + 1, nxt);
;         const char* nA = has_next ? (const char*)g.A + (size_t)nxt.pm * tstep : cA; const char* nB = has_next ? (const char*)g.Bt + (size_t)nxt.pn * tstep : cB;
;         for (int t = 0; t < nt; t += 2) {
;     ...
; #pragma unroll
;         for (int a = 0; a < 2; ++a)
; #pragma unroll
;             for (int b = 0; b < 2; ++b)
; #pragma unroll
;                 for (int m = 0; m < 4; ++m)
; #pragma unroll
;                     for (int n = 0; n < 2; ++n) acc[a][b][m][n] = (f32x4){0.f, 0.f, 0.f, 0.f};
.LBB0_1137:
	s_ashr_i32 s21, s20, 31
	s_lshl_b64 s[22:23], s[20:21], 19
	s_add_u32 s22, s6, s22
	s_addc_u32 s23, s7, s23
	s_and_b64 s[24:25], s[4:5], exec
	s_cselect_b32 s21, s23, s43
	s_cselect_b32 s27, s22, s42
	s_ashr_i32 s19, s18, 31
	s_lshl_b64 s[24:25], s[18:19], 19
	s_add_u32 s24, s48, s24
	s_addc_u32 s25, s49, s25
	s_and_b64 s[46:47], s[4:5], exec
	s_cselect_b32 s19, s25, s45
	s_cselect_b32 s41, s24, s44
	s_add_u32 s42, s42, 0x40080
	s_addc_u32 s43, s43, 0
	s_add_u32 s73, s44, 0x100
	v_mov_b32_e32 v0, 0
	s_addc_u32 s74, s45, 0
	s_mov_b32 s75, -2
	s_waitcnt lgkmcnt(0)
	v_mov_b32_e32 v1, v0
	v_mov_b32_e32 v2, v0
	v_mov_b32_e32 v3, v0
	v_mov_b32_e32 v4, v0
	v_mov_b32_e32 v5, v0
	v_mov_b32_e32 v6, v0
	v_mov_b32_e32 v7, v0
	v_mov_b32_e32 v16, v0
	v_mov_b32_e32 v17, v0
	v_mov_b32_e32 v18, v0
	v_mov_b32_e32 v19, v0
	v_mov_b32_e32 v20, v0
	v_mov_b32_e32 v21, v0
	v_mov_b32_e32 v22, v0
	v_mov_b32_e32 v23, v0
	v_mov_b32_e32 v32, v0
	v_mov_b32_e32 v33, v0
	v_mov_b32_e32 v34, v0
	v_mov_b32_e32 v35, v0
	v_mov_b32_e32 v36, v0
	v_mov_b32_e32 v37, v0
	v_mov_b32_e32 v38, v0
	v_mov_b32_e32 v39, v0
	v_mov_b32_e32 v48, v0
	v_mov_b32_e32 v49, v0
	v_mov_b32_e32 v50, v0
	v_mov_b32_e32 v51, v0
	v_mov_b32_e32 v52, v0
	v_mov_b32_e32 v53, v0
	v_mov_b32_e32 v54, v0
	v_mov_b32_e32 v55, v0
	v_mov_b32_e32 v8, v0
	v_mov_b32_e32 v9, v0
	v_mov_b32_e32 v10, v0
	v_mov_b32_e32 v11, v0
	v_mov_b32_e32 v12, v0
	v_mov_b32_e32 v13, v0
	v_mov_b32_e32 v14, v0
	v_mov_b32_e32 v15, v0
	v_mov_b32_e32 v24, v0
	v_mov_b32_e32 v25, v0
	v_mov_b32_e32 v26, v0
	v_mov_b32_e32 v27, v0
	v_mov_b32_e32 v28, v0
	v_mov_b32_e32 v29, v0
	v_mov_b32_e32 v30, v0
	v_mov_b32_e32 v31, v0
	v_mov_b32_e32 v40, v0
	v_mov_b32_e32 v41, v0
	v_mov_b32_e32 v42, v0
	v_mov_b32_e32 v43, v0
	v_mov_b32_e32 v44, v0
	v_mov_b32_e32 v45, v0
	v_mov_b32_e32 v46, v0
	v_mov_b32_e32 v47, v0
	v_mov_b32_e32 v56, v0
	v_mov_b32_e32 v57, v0
	v_mov_b32_e32 v58, v0
	v_mov_b32_e32 v59, v0
	v_mov_b32_e32 v60, v0
	v_mov_b32_e32 v61, v0
	v_mov_b32_e32 v62, v0
	v_mov_b32_e32 v63, v0
	v_mov_b32_e32 v64, v0
	v_mov_b32_e32 v65, v0
	v_mov_b32_e32 v66, v0
	v_mov_b32_e32 v67, v0
	v_mov_b32_e32 v68, v0
	v_mov_b32_e32 v69, v0
	v_mov_b32_e32 v70, v0
	v_mov_b32_e32 v71, v0
	v_mov_b32_e32 v80, v0
	v_mov_b32_e32 v81, v0
	v_mov_b32_e32 v82, v0
	v_mov_b32_e32 v83, v0
	v_mov_b32_e32 v84, v0
	v_mov_b32_e32 v85, v0
	v_mov_b32_e32 v86, v0
	v_mov_b32_e32 v87, v0
	v_mov_b32_e32 v96, v0
	v_mov_b32_e32 v97, v0
	v_mov_b32_e32 v98, v0
	v_mov_b32_e32 v99, v0
	v_mov_b32_e32 v100, v0
	v_mov_b32_e32 v101, v0
	v_mov_b32_e32 v102, v0
	v_mov_b32_e32 v103, v0
	v_mov_b32_e32 v112, v0
	v_mov_b32_e32 v113, v0
	v_mov_b32_e32 v114, v0
	v_mov_b32_e32 v115, v0
	v_mov_b32_e32 v116, v0
	v_mov_b32_e32 v117, v0
	v_mov_b32_e32 v118, v0
	v_mov_b32_e32 v119, v0
	v_mov_b32_e32 v72, v0
	v_mov_b32_e32 v73, v0
	v_mov_b32_e32 v74, v0
	v_mov_b32_e32 v75, v0
	v_mov_b32_e32 v76, v0
	v_mov_b32_e32 v77, v0
	v_mov_b32_e32 v78, v0
	v_mov_b32_e32 v79, v0
	v_mov_b32_e32 v88, v0
	v_mov_b32_e32 v89, v0
	v_mov_b32_e32 v90, v0
	v_mov_b32_e32 v91, v0
	v_mov_b32_e32 v92, v0
	v_mov_b32_e32 v93, v0
	v_mov_b32_e32 v94, v0
	v_mov_b32_e32 v95, v0
	v_mov_b32_e32 v104, v0
	v_mov_b32_e32 v105, v0
	v_mov_b32_e32 v106, v0
	v_mov_b32_e32 v107, v0
	v_mov_b32_e32 v108, v0
	v_mov_b32_e32 v109, v0
	v_mov_b32_e32 v110, v0
	v_mov_b32_e32 v111, v0
	v_mov_b32_e32 v120, v0
	v_mov_b32_e32 v121, v0
	v_mov_b32_e32 v122, v0
	v_mov_b32_e32 v123, v0
	v_mov_b32_e32 v124, v0
	v_mov_b32_e32 v125, v0
	v_mov_b32_e32 v126, v0
	v_mov_b32_e32 v127, v0
	.p2alignl 6, 3212836864

; template <class Epi, class Sched, bool ALIGN_EPI = false, bool SP2 = false>
; __device__ __forceinline__ void gemm_phase(PG8_LAS unsigned char* lds, const Gemm g, const Sched& S, const Epi& E, int wave_s) {
;     ...
;         const bool has_next = S.next(ui + 1, nxt);
;         const char* nA = has_next ? (const char*)g.A + (size_t)nxt.pm * tstep : cA; const char* nB = has_next ? (const char*)g.Bt + (size_t)nxt.pn * tstep : cB;
;         for (int t = 0; t < nt; t += 2) {
;     ...
; #pragma unroll
;         for (int a = 0; a < 2; ++a)
; #pragma unroll
;             for (int b = 0; b < 2; ++b)
; #pragma unroll
;                 for (int m = 0; m < 4; ++m)
; #pragma unroll
;                     for (int n = 0; n < 2; ++n) acc[a][b][m][n] = (f32x4){0.f, 0.f, 0.f, 0.f};
.LBB0_1256:
	s_ashr_i32 s23, s22, 31
	s_lshl_b64 s[24:25], s[22:23], 19
	s_add_u32 s24, s28, s24
	s_addc_u32 s25, s29, s25
	s_and_b64 s[26:27], s[2:3], exec
	s_cselect_b32 s23, s25, s37
	s_cselect_b32 s64, s24, s36
	s_ashr_i32 s21, s20, 31
	s_lshl_b64 s[26:27], s[20:21], 19
	s_add_u32 s26, s43, s26
	s_addc_u32 s27, s44, s27
	s_and_b64 s[40:41], s[2:3], exec
	s_cselect_b32 s21, s27, s39
	s_cselect_b32 s65, s26, s38
	s_add_u32 s36, s36, 0x40080
	s_addc_u32 s37, s37, 0
	s_add_u32 s66, s38, 0x100
	v_mov_b32_e32 v0, 0
	s_addc_u32 s67, s39, 0
	s_mov_b32 s68, -2
	v_mov_b32_e32 v1, v0
	v_mov_b32_e32 v2, v0
	v_mov_b32_e32 v3, v0
	v_mov_b32_e32 v4, v0
	v_mov_b32_e32 v5, v0
	v_mov_b32_e32 v6, v0
	v_mov_b32_e32 v7, v0
	v_mov_b32_e32 v16, v0
	v_mov_b32_e32 v17, v0
	v_mov_b32_e32 v18, v0
	v_mov_b32_e32 v19, v0
	v_mov_b32_e32 v20, v0
	v_mov_b32_e32 v21, v0
	v_mov_b32_e32 v22, v0
	v_mov_b32_e32 v23, v0
	v_mov_b32_e32 v32, v0
	v_mov_b32_e32 v33, v0
	v_mov_b32_e32 v34, v0
	v_mov_b32_e32 v35, v0
	v_mov_b32_e32 v36, v0
	v_mov_b32_e32 v37, v0
	v_mov_b32_e32 v38, v0
	v_mov_b32_e32 v39, v0
	v_mov_b32_e32 v48, v0
	v_mov_b32_e32 v49, v0
	v_mov_b32_e32 v50, v0
	v_mov_b32_e32 v51, v0
	v_mov_b32_e32 v52, v0
	v_mov_b32_e32 v53, v0
	v_mov_b32_e32 v54, v0
	v_mov_b32_e32 v55, v0
	v_mov_b32_e32 v8, v0
	v_mov_b32_e32 v9, v0
	v_mov_b32_e32 v10, v0
	v_mov_b32_e32 v11, v0
	v_mov_b32_e32 v12, v0
	v_mov_b32_e32 v13, v0
	v_mov_b32_e32 v14, v0
	v_mov_b32_e32 v15, v0
	v_mov_b32_e32 v24, v0
	v_mov_b32_e32 v25, v0
	v_mov_b32_e32 v26, v0
	v_mov_b32_e32 v27, v0
	v_mov_b32_e32 v28, v0
	v_mov_b32_e32 v29, v0
	v_mov_b32_e32 v30, v0
	v_mov_b32_e32 v31, v0
	v_mov_b32_e32 v40, v0
	v_mov_b32_e32 v41, v0
	v_mov_b32_e32 v42, v0
	v_mov_b32_e32 v43, v0
	v_mov_b32_e32 v44, v0
	v_mov_b32_e32 v45, v0
	v_mov_b32_e32 v46, v0
	v_mov_b32_e32 v47, v0
	v_mov_b32_e32 v56, v0
	v_mov_b32_e32 v57, v0
	v_mov_b32_e32 v58, v0
	v_mov_b32_e32 v59, v0
	v_mov_b32_e32 v60, v0
	v_mov_b32_e32 v61, v0
	v_mov_b32_e32 v62, v0
	v_mov_b32_e32 v63, v0
	v_mov_b32_e32 v64, v0
	v_mov_b32_e32 v65, v0
	v_mov_b32_e32 v66, v0
	v_mov_b32_e32 v67, v0
	v_mov_b32_e32 v72, v0
	v_mov_b32_e32 v73, v0
	v_mov_b32_e32 v74, v0
	v_mov_b32_e32 v75, v0
	v_mov_b32_e32 v80, v0
	v_mov_b32_e32 v81, v0
	v_mov_b32_e32 v82, v0
	v_mov_b32_e32 v83, v0
	v_mov_b32_e32 v92, v0
	v_mov_b32_e32 v93, v0
	v_mov_b32_e32 v94, v0
	v_mov_b32_e32 v95, v0
	v_mov_b32_e32 v96, v0
	v_mov_b32_e32 v97, v0
	v_mov_b32_e32 v98, v0
	v_mov_b32_e32 v99, v0
	v_mov_b32_e32 v108, v0
	v_mov_b32_e32 v109, v0
	v_mov_b32_e32 v110, v0
	v_mov_b32_e32 v111, v0
	v_mov_b32_e32 v116, v0
	v_mov_b32_e32 v117, v0
	v_mov_b32_e32 v118, v0
	v_mov_b32_e32 v119, v0
	v_mov_b32_e32 v124, v0
	v_mov_b32_e32 v125, v0
	v_mov_b32_e32 v126, v0
	v_mov_b32_e32 v127, v0
	v_mov_b32_e32 v68, v0
	v_mov_b32_e32 v69, v0
	v_mov_b32_e32 v70, v0
	v_mov_b32_e32 v71, v0
	v_mov_b32_e32 v76, v0
	v_mov_b32_e32 v77, v0
	v_mov_b32_e32 v78, v0
	v_mov_b32_e32 v79, v0
	v_mov_b32_e32 v84, v0
	v_mov_b32_e32 v85, v0
	v_mov_b32_e32 v86, v0
	v_mov_b32_e32 v87, v0
	v_mov_b32_e32 v88, v0
	v_mov_b32_e32 v89, v0
	v_mov_b32_e32 v90, v0
	v_mov_b32_e32 v91, v0
	v_mov_b32_e32 v100, v0
	v_mov_b32_e32 v101, v0
	v_mov_b32_e32 v102, v0
	v_mov_b32_e32 v103, v0
	v_mov_b32_e32 v104, v0
	v_mov_b32_e32 v105, v0
	v_mov_b32_e32 v106, v0
	v_mov_b32_e32 v107, v0
	v_mov_b32_e32 v112, v0
	v_mov_b32_e32 v113, v0
	v_mov_b32_e32 v114, v0
	v_mov_b32_e32 v115, v0
	v_mov_b32_e32 v120, v0
	v_mov_b32_e32 v121, v0
	v_mov_b32_e32 v122, v0
	v_mov_b32_e32 v123, v0
	.p2alignl 6, 3212836864

; template <class Epi, class Sched, bool ALIGN_EPI = false, bool SP2 = false>
; __device__ __forceinline__ void gemm_phase(PG8_LAS unsigned char* lds, const Gemm g, const Sched& S, const Epi& E, int wave_s) {
;     ...
; #pragma unroll
;         for (int a = 0; a < 2; ++a)
; #pragma unroll
;             for (int b = 0; b < 2; ++b)
; #pragma unroll
;                 for (int m = 0; m < 4; ++m)
; #pragma unroll
;                     for (int n = 0; n < 2; ++n) acc[a][b][m][n] = (f32x4){0.f, 0.f, 0.f, 0.f};
.LBB0_1345:
	s_add_u32 s58, s20, 0x100
	v_mov_b32_e32 v0, 0
	s_addc_u32 s59, s21, 0
	s_mov_b32 s60, -2
	s_waitcnt lgkmcnt(0)
	v_mov_b32_e32 v1, v0
	v_mov_b32_e32 v2, v0
	v_mov_b32_e32 v3, v0
	v_mov_b32_e32 v4, v0
	v_mov_b32_e32 v5, v0
	v_mov_b32_e32 v6, v0
	v_mov_b32_e32 v7, v0
	v_mov_b32_e32 v16, v0
	v_mov_b32_e32 v17, v0
	v_mov_b32_e32 v18, v0
	v_mov_b32_e32 v19, v0
	v_mov_b32_e32 v20, v0
	v_mov_b32_e32 v21, v0
	v_mov_b32_e32 v22, v0
	v_mov_b32_e32 v23, v0
	v_mov_b32_e32 v32, v0
	v_mov_b32_e32 v33, v0
	v_mov_b32_e32 v34, v0
	v_mov_b32_e32 v35, v0
	v_mov_b32_e32 v36, v0
	v_mov_b32_e32 v37, v0
	v_mov_b32_e32 v38, v0
	v_mov_b32_e32 v39, v0
	v_mov_b32_e32 v48, v0
	v_mov_b32_e32 v49, v0
	v_mov_b32_e32 v50, v0
	v_mov_b32_e32 v51, v0
	v_mov_b32_e32 v52, v0
	v_mov_b32_e32 v53, v0
	v_mov_b32_e32 v54, v0
	v_mov_b32_e32 v55, v0
	v_mov_b32_e32 v8, v0
	v_mov_b32_e32 v9, v0
	v_mov_b32_e32 v10, v0
	v_mov_b32_e32 v11, v0
	v_mov_b32_e32 v12, v0
	v_mov_b32_e32 v13, v0
	v_mov_b32_e32 v14, v0
	v_mov_b32_e32 v15, v0
	v_mov_b32_e32 v24, v0
	v_mov_b32_e32 v25, v0
	v_mov_b32_e32 v26, v0
	v_mov_b32_e32 v27, v0
	v_mov_b32_e32 v28, v0
	v_mov_b32_e32 v29, v0
	v_mov_b32_e32 v30, v0
	v_mov_b32_e32 v31, v0
	v_mov_b32_e32 v40, v0
	v_mov_b32_e32 v41, v0
	v_mov_b32_e32 v42, v0
	v_mov_b32_e32 v43, v0
	v_mov_b32_e32 v44, v0
	v_mov_b32_e32 v45, v0
	v_mov_b32_e32 v46, v0
	v_mov_b32_e32 v47, v0
	v_mov_b32_e32 v56, v0
	v_mov_b32_e32 v57, v0
	v_mov_b32_e32 v58, v0
	v_mov_b32_e32 v59, v0
	v_mov_b32_e32 v60, v0
	v_mov_b32_e32 v61, v0
	v_mov_b32_e32 v62, v0
	v_mov_b32_e32 v63, v0
	v_mov_b32_e32 v64, v0
	v_mov_b32_e32 v65, v0
	v_mov_b32_e32 v66, v0
	v_mov_b32_e32 v67, v0
	v_mov_b32_e32 v68, v0
	v_mov_b32_e32 v69, v0
	v_mov_b32_e32 v70, v0
	v_mov_b32_e32 v71, v0
	v_mov_b32_e32 v80, v0
	v_mov_b32_e32 v81, v0
	v_mov_b32_e32 v82, v0
	v_mov_b32_e32 v83, v0
	v_mov_b32_e32 v84, v0
	v_mov_b32_e32 v85, v0
	v_mov_b32_e32 v86, v0
	v_mov_b32_e32 v87, v0
	v_mov_b32_e32 v96, v0
	v_mov_b32_e32 v97, v0
	v_mov_b32_e32 v98, v0
	v_mov_b32_e32 v99, v0
	v_mov_b32_e32 v100, v0
	v_mov_b32_e32 v101, v0
	v_mov_b32_e32 v102, v0
	v_mov_b32_e32 v103, v0
	v_mov_b32_e32 v112, v0
	v_mov_b32_e32 v113, v0
	v_mov_b32_e32 v114, v0
	v_mov_b32_e32 v115, v0
	v_mov_b32_e32 v116, v0
	v_mov_b32_e32 v117, v0
	v_mov_b32_e32 v118, v0
	v_mov_b32_e32 v119, v0
	v_mov_b32_e32 v72, v0
	v_mov_b32_e32 v73, v0
	v_mov_b32_e32 v74, v0
	v_mov_b32_e32 v75, v0
	v_mov_b32_e32 v76, v0
	v_mov_b32_e32 v77, v0
	v_mov_b32_e32 v78, v0
	v_mov_b32_e32 v79, v0
	v_mov_b32_e32 v88, v0
	v_mov_b32_e32 v89, v0
	v_mov_b32_e32 v90, v0
	v_mov_b32_e32 v91, v0
	v_mov_b32_e32 v92, v0
	v_mov_b32_e32 v93, v0
	v_mov_b32_e32 v94, v0
	v_mov_b32_e32 v95, v0
	v_mov_b32_e32 v104, v0
	v_mov_b32_e32 v105, v0
	v_mov_b32_e32 v106, v0
	v_mov_b32_e32 v107, v0
	v_mov_b32_e32 v108, v0
	v_mov_b32_e32 v109, v0
	v_mov_b32_e32 v110, v0
	v_mov_b32_e32 v111, v0
	v_mov_b32_e32 v120, v0
	v_mov_b32_e32 v121, v0
	v_mov_b32_e32 v122, v0
	v_mov_b32_e32 v123, v0
	v_mov_b32_e32 v124, v0
	v_mov_b32_e32 v125, v0
	v_mov_b32_e32 v126, v0
	v_mov_b32_e32 v127, v0
	.p2alignl 6, 3212836864
